# attention A and B: output tile transposed through wave-private LDS, 4 full-line dwordx4 stores instead of 8 dwordx2
# speedup vs baseline: 1.0163x; 1.0110x over previous
; __device__ __forceinline__ unsigned pk2(float lo, float hi) { f32x2_t v = {lo, hi}; bf16x2_t b = __builtin_convertvector(v, bf16x2_t); return __builtin_bit_cast(unsigned, b); }
; __device__ __forceinline__ void attn_store(bf16_t* orow, const f32x16& o0, const f32x16& o1, float inv, int hi) {
; #pragma unroll
;     for (int g = 0; g < 4; ++g) {
;         u32x2 w0, w1;
;         w0[0] = pk2(o0[4 * g] * inv, o0[4 * g + 1] * inv); w0[1] = pk2(o0[4 * g + 2] * inv, o0[4 * g + 3] * inv);
;         w1[0] = pk2(o1[4 * g] * inv, o1[4 * g + 1] * inv); w1[1] = pk2(o1[4 * g + 2] * inv, o1[4 * g + 3] * inv);
;         *(u32x2*)(orow + 8 * g + 4 * hi) = w0; *(u32x2*)(orow + 32 + 8 * g + 4 * hi) = w1;
;     }
; }
; __device__ __forceinline__ void attnB_phase(const bf16_t* QB, const bf16_t* KB, const bf16_t* VB, bf16_t* YB, const float* relb, LAS unsigned char* lds, int gw, int ngw, int lane, int wave) {
;     ...
;         const float lt_ = l + __shfl_xor(l, 32), inv = 1.0f / lt_;
;         attn_store(YB + (rowb + tq) * 768 + 256 + h * 64, o0, o1, inv, hi);
.LBB0_21:
	v_cmp_lt_i32_e32 vcc, v188, v189
	s_movk_i32 s2, 0x600
	s_lshl_b32 s34, s15, 1
	v_cndmask_b32_e32 v0, v34, v188, vcc
	v_lshlrev_b32_e32 v0, 2, v0
	ds_bpermute_b32 v0, v0, v182
	v_lshlrev_b32_e32 v36, 2, v171
	ds_bpermute_b32 v36, v36, v166
	s_add_i32 s20, s20, s28
	s_waitcnt lgkmcnt(0)
	v_add_f32_e32 v0, v182, v0
	v_div_scale_f32 v34, s[0:1], v0, v0, 1.0
	v_rcp_f32_e32 v35, v34
	s_nop 0
	v_fma_f32 v37, -v34, v35, 1.0
	v_fmac_f32_e32 v35, v37, v35
	v_div_scale_f32 v37, vcc, 1.0, v0, 1.0
	v_mul_f32_e32 v38, v37, v35
	v_fma_f32 v39, -v34, v38, v37
	v_fmac_f32_e32 v38, v39, v35
	v_fma_f32 v34, -v34, v38, v37
	v_lshl_add_u32 v39, v172, 1, s34
	v_div_fmas_f32 v34, v34, v35, v38
	v_div_fixup_f32 v34, v34, v0, 1.0
	v_pk_mul_f32 v[18:19], v[18:19], v[34:35] op_sel_hi:[1,0]
	v_pk_mul_f32 v[20:21], v[20:21], v[34:35] op_sel_hi:[1,0]
	v_pk_mul_f32 v[22:23], v[22:23], v[34:35] op_sel_hi:[1,0]
	v_pk_mul_f32 v[24:25], v[24:25], v[34:35] op_sel_hi:[1,0]
	v_pk_mul_f32 v[26:27], v[26:27], v[34:35] op_sel_hi:[1,0]
	v_pk_mul_f32 v[28:29], v[28:29], v[34:35] op_sel_hi:[1,0]
	v_pk_mul_f32 v[30:31], v[30:31], v[34:35] op_sel_hi:[1,0]
	v_pk_mul_f32 v[32:33], v[32:33], v[34:35] op_sel_hi:[1,0]
	v_pk_mul_f32 v[2:3], v[2:3], v[34:35] op_sel_hi:[1,0]
	v_pk_mul_f32 v[4:5], v[4:5], v[34:35] op_sel_hi:[1,0]
	v_pk_mul_f32 v[6:7], v[6:7], v[34:35] op_sel_hi:[1,0]
	v_pk_mul_f32 v[8:9], v[8:9], v[34:35] op_sel_hi:[1,0]
	v_pk_mul_f32 v[10:11], v[10:11], v[34:35] op_sel_hi:[1,0]
	v_pk_mul_f32 v[12:13], v[12:13], v[34:35] op_sel_hi:[1,0]
	v_pk_mul_f32 v[14:15], v[14:15], v[34:35] op_sel_hi:[1,0]
	v_pk_mul_f32 v[16:17], v[16:17], v[34:35] op_sel_hi:[1,0]
	v_cvt_pk_bf16_f32 v66, v18, v19
	v_cvt_pk_bf16_f32 v67, v20, v21
	v_cvt_pk_bf16_f32 v68, v22, v23
	v_cvt_pk_bf16_f32 v69, v24, v25
	v_cvt_pk_bf16_f32 v70, v26, v27
	v_cvt_pk_bf16_f32 v71, v28, v29
	v_cvt_pk_bf16_f32 v72, v30, v31
	v_cvt_pk_bf16_f32 v73, v32, v33
	v_cvt_pk_bf16_f32 v74, v2, v3
	v_cvt_pk_bf16_f32 v75, v4, v5
	v_cvt_pk_bf16_f32 v76, v6, v7
	v_cvt_pk_bf16_f32 v77, v8, v9
	v_cvt_pk_bf16_f32 v78, v10, v11
	v_cvt_pk_bf16_f32 v79, v12, v13
	v_cvt_pk_bf16_f32 v80, v14, v15
	v_cvt_pk_bf16_f32 v81, v16, v17
	v_lshlrev_b32_e32 v37, 1, v162
	v_sub_u32_e32 v37, v180, v37
	v_add_u32_e32 v37, 0x2000, v37
	ds_write2_b64 v37, v[66:67], v[74:75] offset0:0 offset1:8
	ds_write2_b64 v37, v[68:69], v[76:77] offset0:2 offset1:10
	ds_write2_b64 v37, v[70:71], v[78:79] offset0:4 offset1:12
	ds_write2_b64 v37, v[72:73], v[80:81] offset0:6 offset1:14
	ds_read_b128 v[2:5], v179 offset:8192
	ds_read_b128 v[6:9], v179 offset:9344
	ds_read_b128 v[10:13], v179 offset:10496
	ds_read_b128 v[14:17], v179 offset:11648
	v_mad_u32_u24 v36, v36, s2, v39
	v_add_u32_e32 v37, 0x3000, v36
	v_add_u32_e32 v38, 0x18000, v36
	v_add_u32_e32 v39, 0x1b000, v36
	v_readlane_b32 s0, v249, 49
	s_waitcnt lgkmcnt(0)
	global_store_dwordx4 v36, v[2:5], s[56:57] offset:512
	global_store_dwordx4 v37, v[6:9], s[56:57] offset:512
	global_store_dwordx4 v38, v[10:13], s[56:57] offset:512
	global_store_dwordx4 v39, v[14:17], s[56:57] offset:512
	s_add_i32 s22, s22, s0
	s_cmpk_gt_i32 s20, 0x1fff
	s_cbranch_scc1 .LBB0_45

; __device__ __forceinline__ unsigned pk2(float lo, float hi) { f32x2_t v = {lo, hi}; bf16x2_t b = __builtin_convertvector(v, bf16x2_t); return __builtin_bit_cast(unsigned, b); }
; __device__ __forceinline__ void attn_store(bf16_t* orow, const f32x16& o0, const f32x16& o1, float inv, int hi) {
; #pragma unroll
;     for (int g = 0; g < 4; ++g) {
;         u32x2 w0, w1;
;         w0[0] = pk2(o0[4 * g] * inv, o0[4 * g + 1] * inv); w0[1] = pk2(o0[4 * g + 2] * inv, o0[4 * g + 3] * inv);
;         w1[0] = pk2(o1[4 * g] * inv, o1[4 * g + 1] * inv); w1[1] = pk2(o1[4 * g + 2] * inv, o1[4 * g + 3] * inv);
;         *(u32x2*)(orow + 8 * g + 4 * hi) = w0; *(u32x2*)(orow + 32 + 8 * g + 4 * hi) = w1;
;     }
; }
; __device__ __forceinline__ void attnA_phase(const bf16_t* QA, bf16_t* OA, const bf16_t* KA, const bf16_t* VA, float* LSE, LAS unsigned char* lds, int gw, int ngw, int lane, int wave) {
;     ...
;         const float lt_ = l + __shfl_xor(l, 32), inv = 1.0f / lt_;
;         attn_store(OA + (rowb + tq) * 768 + h * 64, o0, o1, inv, hi);
;         if (hi == 0) LSE[(size_t)h * MTOK + (rowb + tq)] = m + __builtin_amdgcn_logf(lt_);
.LBB0_100:
	v_cmp_lt_i32_e32 vcc, v222, v223
	v_readlane_b32 s44, v250, 1
	v_readlane_b32 s56, v250, 13
	v_cndmask_b32_e32 v0, v221, v222, vcc
	v_lshlrev_b32_e32 v0, 2, v0
	ds_bpermute_b32 v0, v0, v193
	v_readlane_b32 s57, v250, 14
	v_mov_b32_e32 v197, v1
	v_readlane_b32 s45, v250, 2
	v_lshl_add_u64 v[2:3], v[200:201], 1, s[56:57]
	s_waitcnt lgkmcnt(0)
	v_add_f32_e32 v0, v193, v0
	v_div_scale_f32 v4, s[10:11], v0, v0, 1.0
	v_rcp_f32_e32 v5, v4
	v_div_scale_f32 v6, vcc, 1.0, v0, 1.0
	v_lshl_add_u64 v[2:3], s[12:13], 1, v[2:3]
	v_fma_f32 v7, -v4, v5, 1.0
	v_fmac_f32_e32 v5, v7, v5
	v_mul_f32_e32 v7, v6, v5
	v_fma_f32 v8, -v4, v7, v6
	v_fmac_f32_e32 v7, v8, v5
	v_fma_f32 v4, -v4, v7, v6
	v_div_fmas_f32 v4, v4, v5, v7
	v_div_fixup_f32 v4, v4, v0, 1.0
	v_pk_mul_f32 v[32:33], v[32:33], v[4:5] op_sel_hi:[1,0]
	v_pk_mul_f32 v[34:35], v[34:35], v[4:5] op_sel_hi:[1,0]
	v_pk_mul_f32 v[36:37], v[36:37], v[4:5] op_sel_hi:[1,0]
	v_pk_mul_f32 v[38:39], v[38:39], v[4:5] op_sel_hi:[1,0]
	v_pk_mul_f32 v[40:41], v[40:41], v[4:5] op_sel_hi:[1,0]
	v_pk_mul_f32 v[42:43], v[42:43], v[4:5] op_sel_hi:[1,0]
	v_pk_mul_f32 v[44:45], v[44:45], v[4:5] op_sel_hi:[1,0]
	v_pk_mul_f32 v[46:47], v[46:47], v[4:5] op_sel_hi:[1,0]
	v_pk_mul_f32 v[16:17], v[16:17], v[4:5] op_sel_hi:[1,0]
	v_pk_mul_f32 v[18:19], v[18:19], v[4:5] op_sel_hi:[1,0]
	v_pk_mul_f32 v[20:21], v[20:21], v[4:5] op_sel_hi:[1,0]
	v_pk_mul_f32 v[22:23], v[22:23], v[4:5] op_sel_hi:[1,0]
	v_pk_mul_f32 v[24:25], v[24:25], v[4:5] op_sel_hi:[1,0]
	v_pk_mul_f32 v[26:27], v[26:27], v[4:5] op_sel_hi:[1,0]
	v_pk_mul_f32 v[28:29], v[28:29], v[4:5] op_sel_hi:[1,0]
	v_pk_mul_f32 v[30:31], v[30:31], v[4:5] op_sel_hi:[1,0]
	v_cvt_pk_bf16_f32 v48, v32, v33
	v_cvt_pk_bf16_f32 v49, v34, v35
	v_cvt_pk_bf16_f32 v50, v36, v37
	v_cvt_pk_bf16_f32 v51, v38, v39
	v_cvt_pk_bf16_f32 v52, v40, v41
	v_cvt_pk_bf16_f32 v53, v42, v43
	v_cvt_pk_bf16_f32 v54, v44, v45
	v_cvt_pk_bf16_f32 v55, v46, v47
	v_cvt_pk_bf16_f32 v56, v16, v17
	v_cvt_pk_bf16_f32 v57, v18, v19
	v_cvt_pk_bf16_f32 v58, v20, v21
	v_cvt_pk_bf16_f32 v59, v22, v23
	v_cvt_pk_bf16_f32 v60, v24, v25
	v_cvt_pk_bf16_f32 v61, v26, v27
	v_cvt_pk_bf16_f32 v62, v28, v29
	v_cvt_pk_bf16_f32 v63, v30, v31
	v_sub_u32_e32 v6, v209, v196
	v_add_u32_e32 v6, 0x2000, v6
	ds_write2_b64 v6, v[48:49], v[56:57] offset0:0 offset1:8
	ds_write2_b64 v6, v[50:51], v[58:59] offset0:2 offset1:10
	ds_write2_b64 v6, v[52:53], v[60:61] offset0:4 offset1:12
	ds_write2_b64 v6, v[54:55], v[62:63] offset0:6 offset1:14
	ds_read_b128 v[64:67], v208 offset:8192
	ds_read_b128 v[68:71], v208 offset:9344
	ds_read_b128 v[72:75], v208 offset:10496
	ds_read_b128 v[76:79], v208 offset:11648
	s_sub_i32 s10, -2, s23
	s_lshl_b32 s11, 0x3000, s19
	v_lshl_or_b32 v7, s10, 5, v204
	v_lshlrev_b32_e32 v7, s19, v7
	v_add_u32_e32 v7, s20, v7
	v_mad_u32_u24 v7, v7, s33, v202
	v_lshlrev_b32_e32 v7, 1, v7
	v_add_u32_e32 v8, s11, v7
	v_add_u32_e32 v9, s11, v8
	v_add_u32_e32 v10, s11, v9
	s_waitcnt lgkmcnt(0)
	global_store_dwordx4 v7, v[64:67], s[56:57]
	global_store_dwordx4 v8, v[68:71], s[56:57]
	global_store_dwordx4 v9, v[72:75], s[56:57]
	global_store_dwordx4 v10, v[76:79], s[56:57]
	v_readlane_b32 s46, v250, 3
	v_readlane_b32 s47, v250, 4
	v_readlane_b32 s48, v250, 5
	v_readlane_b32 s49, v250, 6
	v_readlane_b32 s50, v250, 7
	v_readlane_b32 s51, v250, 8
	v_readlane_b32 s52, v250, 9
	v_readlane_b32 s53, v250, 10
	v_readlane_b32 s54, v250, 11
	v_readlane_b32 s55, v250, 12
	v_readlane_b32 s58, v250, 15
	v_readlane_b32 s59, v250, 16
	s_mov_b64 s[12:13], exec
	v_readlane_b32 s10, v248, 24
	v_readlane_b32 s11, v248, 25
	s_and_b64 s[10:11], s[12:13], s[10:11]
	s_mov_b64 exec, s[10:11]
	s_cbranch_execz .LBB0_66
	s_ashr_i32 s10, s9, 6
	v_log_f32_e32 v0, v0
	s_ashr_i32 s11, s10, 31
	s_lshl_b64 s[10:11], s[10:11], 17
	v_readlane_b32 s14, v250, 31
	v_readlane_b32 s15, v250, 32
	s_add_u32 s10, s14, s10
	s_addc_u32 s11, s15, s11
	v_add_f32_e32 v0, v211, v0
	v_lshl_add_u64 v[2:3], v[198:199], 2, s[10:11]
	global_store_dword v[2:3], v0, off
	s_branch .LBB0_66
